# conv LayerNorm stage: DPP intra-row reductions, gate load hoisted to iteration start, batched silu
# speedup vs baseline: 1.0031x; 1.0031x over previous
; DEV unsigned pk_bf16(float lo, float hi) { const bf16x2_t v = __builtin_convertvector((f32x2){lo, hi}, bf16x2_t); return __builtin_bit_cast(unsigned, v); }
; DEV float bflo(unsigned u) { return __uint_as_float(u << 16); }
; DEV float bfhi(unsigned u) { return __uint_as_float(u & 0xffff0000u); }
; DEV float siluf_(float v) { return v * __builtin_amdgcn_rcpf(1.0f + __expf(-v)); }
; DEV void conv_item(const Params& p, int l, int tile, char* smem, int dry) {
;     ...
; #pragma unroll 1
;     for (int t = wid; t < 32; t += 8) {
;         const f32x4 x0 = *(const f32x4*)(sout + t * 512 + lane * 8), x1 = *(const f32x4*)(sout + t * 512 + lane * 8 + 4);
;         float sm = (x0[0] + x0[1]) + (x0[2] + x0[3]) + (x1[0] + x1[1]) + (x1[2] + x1[3]);
;         const float mean = wave_sum(sm) * (1.0f / 512.0f);
;         const f32x4 d0 = x0 - mean, d1 = x1 - mean;
;         float sq = (d0[0] * d0[0] + d0[1] * d0[1]) + (d0[2] * d0[2] + d0[3] * d0[3]) + (d1[0] * d1[0] + d1[1] * d1[1]) + (d1[2] * d1[2] + d1[3] * d1[3]);
;         const float rstd = rsqrtf(wave_sum(sq) * (1.0f / 512.0f) + 1e-5f);
;         bf16_t* yp = Y + (size_t)(t0 + t) * 2048 + 1024 + lane * 8;
;         const u32x4 g = *(const u32x4*)yp;
;         f32x4 y0 = d0 * rstd * g0 + b0, y1 = d1 * rstd * g1 + b1;
;         float o[8];
; #pragma unroll
;         for (int j = 0; j < 4; ++j) { o[j] = siluf_(y0[j]); o[4 + j] = siluf_(y1[j]); }
; #pragma unroll
;         for (int j = 0; j < 4; ++j) { o[2 * j] *= bflo(g[j]); o[2 * j + 1] *= bfhi(g[j]); }
;         if (!dry) *(u32x4*)yp = (u32x4){pk_bf16(o[0], o[1]), pk_bf16(o[2], o[3]), pk_bf16(o[4], o[5]), pk_bf16(o[6], o[7])};
;     }
.LBB0_400:
	ds_read_b128 v[20:23], v30
	ds_read_b128 v[16:19], v30 offset:16
	v_add_u32_e32 v30, 0x4000, v30
	v_add_u32_e32 v32, s28, v29
	v_ashrrev_i32_e32 v33, 31, v32
	v_lshlrev_b64 v[32:33], 12, v[32:33]
	v_lshl_add_u64 v[32:33], s[46:47], 0, v[32:33]
	v_lshl_add_u64 v[32:33], v[32:33], 0, v[160:161]
	v_add_co_u32_e32 v36, vcc, s33, v32
	s_nop 1
	v_addc_co_u32_e32 v37, vcc, 0, v33, vcc
	global_load_dwordx4 v[96:99], v[36:37], off offset:2048
	v_cmp_lt_i32_e32 vcc, 23, v29
	s_or_b64 s[8:9], vcc, s[8:9]
	s_waitcnt lgkmcnt(0)
	v_pk_add_f32 v[32:33], v[20:21], v[22:23]
	v_pk_add_f32 v[34:35], v[16:17], v[18:19]
	v_pk_add_f32 v[32:33], v[32:33], v[34:35]
	s_nop 0
	v_add_f32_e32 v24, v32, v33
	s_nop 1
	v_add_f32_dpp v24, v24, v24 quad_perm:[1,0,3,2] row_mask:0xf bank_mask:0xf bound_ctrl:1
	s_nop 1
	v_add_f32_dpp v24, v24, v24 quad_perm:[2,3,0,1] row_mask:0xf bank_mask:0xf bound_ctrl:1
	s_nop 1
	v_add_f32_dpp v24, v24, v24 row_half_mirror row_mask:0xf bank_mask:0xf bound_ctrl:1
	s_nop 1
	v_add_f32_dpp v24, v24, v24 row_mirror row_mask:0xf bank_mask:0xf bound_ctrl:1
	ds_bpermute_b32 v31, v82, v24
	s_waitcnt lgkmcnt(0)
	v_add_f32_e32 v24, v24, v31
	ds_bpermute_b32 v31, v83, v24
	s_waitcnt lgkmcnt(0)
	v_add_f32_e32 v24, v24, v31
	v_mul_f32_e32 v32, 0xbb000000, v24
	v_pk_add_f32 v[20:21], v[20:21], v[32:33] op_sel_hi:[1,0]
	v_pk_add_f32 v[22:23], v[22:23], v[32:33] op_sel_hi:[1,0]
	v_pk_add_f32 v[16:17], v[16:17], v[32:33] op_sel_hi:[1,0]
	v_pk_add_f32 v[18:19], v[18:19], v[32:33] op_sel_hi:[1,0]
	v_pk_mul_f32 v[34:35], v[20:21], v[20:21]
	v_pk_mul_f32 v[38:39], v[22:23], v[22:23]
	v_pk_fma_f32 v[34:35], v[16:17], v[16:17], v[34:35]
	v_pk_fma_f32 v[38:39], v[18:19], v[18:19], v[38:39]
	v_pk_add_f32 v[34:35], v[34:35], v[38:39]
	s_nop 0
	v_add_f32_e32 v24, v34, v35
	s_nop 1
	v_add_f32_dpp v24, v24, v24 quad_perm:[1,0,3,2] row_mask:0xf bank_mask:0xf bound_ctrl:1
	s_nop 1
	v_add_f32_dpp v24, v24, v24 quad_perm:[2,3,0,1] row_mask:0xf bank_mask:0xf bound_ctrl:1
	s_nop 1
	v_add_f32_dpp v24, v24, v24 row_half_mirror row_mask:0xf bank_mask:0xf bound_ctrl:1
	s_nop 1
	v_add_f32_dpp v24, v24, v24 row_mirror row_mask:0xf bank_mask:0xf bound_ctrl:1
	ds_bpermute_b32 v31, v82, v24
	s_waitcnt lgkmcnt(0)
	v_add_f32_e32 v24, v24, v31
	ds_bpermute_b32 v31, v83, v24
	s_waitcnt lgkmcnt(0)
	v_add_f32_e32 v24, v24, v31
	v_fmamk_f32 v24, v24, 0x3b000000, v179
	v_rsq_f32_e32 v24, v24
	s_nop 1
	v_pk_mul_f32 v[20:21], v[20:21], v[24:25] op_sel_hi:[1,0]
	v_pk_mul_f32 v[22:23], v[22:23], v[24:25] op_sel_hi:[1,0]
	v_pk_mul_f32 v[16:17], v[16:17], v[24:25] op_sel_hi:[1,0]
	v_pk_mul_f32 v[18:19], v[18:19], v[24:25] op_sel_hi:[1,0]
	s_waitcnt vmcnt(1)
	v_pk_fma_f32 v[20:21], v[12:13], v[20:21], v[4:5]
	v_pk_fma_f32 v[22:23], v[14:15], v[22:23], v[6:7]
	v_pk_fma_f32 v[16:17], v[8:9], v[16:17], v[0:1]
	v_pk_fma_f32 v[18:19], v[10:11], v[18:19], v[2:3]
	v_mul_f32_e32 v32, 0xbfb8aa3b, v20
	v_mul_f32_e32 v33, 0xbfb8aa3b, v21
	v_mul_f32_e32 v34, 0xbfb8aa3b, v22
	v_mul_f32_e32 v35, 0xbfb8aa3b, v23
	v_mul_f32_e32 v38, 0xbfb8aa3b, v16
	v_mul_f32_e32 v39, 0xbfb8aa3b, v17
	v_mul_f32_e32 v100, 0xbfb8aa3b, v18
	v_mul_f32_e32 v101, 0xbfb8aa3b, v19
	v_exp_f32_e32 v32, v32
	v_exp_f32_e32 v33, v33
	v_exp_f32_e32 v34, v34
	v_exp_f32_e32 v35, v35
	v_exp_f32_e32 v38, v38
	v_exp_f32_e32 v39, v39
	v_exp_f32_e32 v100, v100
	v_exp_f32_e32 v101, v101
	v_add_f32_e32 v32, 1.0, v32
	v_add_f32_e32 v33, 1.0, v33
	v_add_f32_e32 v34, 1.0, v34
	v_add_f32_e32 v35, 1.0, v35
	v_add_f32_e32 v38, 1.0, v38
	v_add_f32_e32 v39, 1.0, v39
	v_add_f32_e32 v100, 1.0, v100
	v_add_f32_e32 v101, 1.0, v101
	v_rcp_f32_e32 v32, v32
	v_rcp_f32_e32 v33, v33
	v_rcp_f32_e32 v34, v34
	v_rcp_f32_e32 v35, v35
	v_rcp_f32_e32 v38, v38
	v_rcp_f32_e32 v39, v39
	v_rcp_f32_e32 v100, v100
	v_rcp_f32_e32 v101, v101
	v_pk_mul_f32 v[20:21], v[20:21], v[32:33]
	v_pk_mul_f32 v[22:23], v[22:23], v[34:35]
	v_pk_mul_f32 v[16:17], v[16:17], v[38:39]
	v_pk_mul_f32 v[18:19], v[18:19], v[100:101]
	s_waitcnt vmcnt(0)
	v_lshlrev_b32_e32 v32, 16, v96
	v_and_b32_e32 v33, 0xffff0000, v96
	v_pk_mul_f32 v[20:21], v[20:21], v[32:33]
	v_lshlrev_b32_e32 v32, 16, v97
	v_and_b32_e32 v33, 0xffff0000, v97
	v_pk_mul_f32 v[22:23], v[22:23], v[32:33]
	v_lshlrev_b32_e32 v32, 16, v98
	v_and_b32_e32 v33, 0xffff0000, v98
	v_pk_mul_f32 v[16:17], v[16:17], v[32:33]
	v_lshlrev_b32_e32 v32, 16, v99
	v_and_b32_e32 v33, 0xffff0000, v99
	v_pk_mul_f32 v[18:19], v[18:19], v[32:33]
	v_cvt_pk_bf16_f32 v32, v20, v21
	v_cvt_pk_bf16_f32 v33, v22, v23
	v_cvt_pk_bf16_f32 v34, v16, v17
	v_cvt_pk_bf16_f32 v35, v18, v19
	global_store_dwordx4 v[36:37], v[32:35], off offset:2048
	v_add_u32_e32 v29, 8, v29
	s_andn2_b64 exec, exec, s[8:9]
	s_cbranch_execnz .LBB0_400
	s_branch .LBB0_392
